# SwiGLU activations (the down projection's A operand) stored with the default cache policy instead of nontemporal
# speedup vs baseline: 1.0039x; 1.0039x over previous
.LBB0_798:
	s_lshl_b32 s51, s36, 15
	s_lshl_b32 s4, s33, 11
	s_add_u32 s4, s14, s4
	s_addc_u32 s5, s15, 0
	s_mov_b64 s[36:37], s[4:5]
	v_pk_mul_f32 v[146:147], v[150:151], v[146:147]
	v_lshl_add_u64 v[152:153], s[36:37], 0, v[80:81]
	global_load_dwordx2 v[170:171], v[152:153], off
	s_add_u32 s36, s4, 0x80
	s_addc_u32 s37, s5, 0
	v_pk_mul_f32 v[144:145], v[148:149], v[144:145]
	v_lshl_add_u64 v[152:153], s[36:37], 0, v[80:81]
	global_load_dwordx2 v[164:165], v[152:153], off
	s_add_u32 s36, s4, 0x100
	s_addc_u32 s37, s5, 0
	s_mul_i32 s33, s33, 0x2c0000
	v_lshl_add_u64 v[152:153], s[36:37], 0, v[80:81]
	global_load_dwordx2 v[162:163], v[152:153], off
	s_add_u32 s36, s4, 0x180
	s_addc_u32 s37, s5, 0
	v_pk_mul_f32 v[138:139], v[142:143], v[138:139]
	v_lshl_add_u64 v[152:153], s[36:37], 0, v[80:81]
	global_load_dwordx2 v[160:161], v[152:153], off
	s_add_u32 s36, s4, 0x400
	s_addc_u32 s37, s5, 0
	v_pk_mul_f32 v[136:137], v[140:141], v[136:137]
	v_lshl_add_u64 v[152:153], s[36:37], 0, v[80:81]
	s_add_u32 s36, s4, 0x480
	s_addc_u32 s37, s5, 0
	global_load_dwordx2 v[158:159], v[152:153], off
	v_pk_mul_f32 v[130:131], v[134:135], v[130:131]
	v_lshl_add_u64 v[152:153], s[36:37], 0, v[80:81]
	s_add_u32 s36, s4, 0x500
	s_addc_u32 s37, s5, 0
	s_add_u32 s4, s4, 0x580
	global_load_dwordx2 v[156:157], v[152:153], off
	s_addc_u32 s5, s5, 0
	v_lshl_add_u64 v[152:153], s[36:37], 0, v[80:81]
	global_load_dwordx2 v[154:155], v[152:153], off
	s_add_i32 s33, s33, s51
	v_lshl_add_u64 v[152:153], s[4:5], 0, v[80:81]
	global_load_dwordx2 v[152:153], v[152:153], off
	s_add_u32 s4, s20, s33
	s_addc_u32 s5, s68, 0
	s_mov_b64 s[36:37], s[4:5]
	v_pk_mul_f32 v[128:129], v[132:133], v[128:129]
	v_pk_mul_f32 v[122:123], v[126:127], v[122:123]
	v_pk_mul_f32 v[120:121], v[124:125], v[120:121]
	s_add_u32 s4, s4, 0x800
	s_addc_u32 s5, s5, 0
	v_pk_mul_f32 v[114:115], v[118:119], v[114:115]
	v_pk_mul_f32 v[112:113], v[116:117], v[112:113]
	v_pk_mul_f32 v[106:107], v[110:111], v[106:107]
	v_pk_mul_f32 v[104:105], v[108:109], v[104:105]
	v_pk_mul_f32 v[74:75], v[78:79], v[74:75]
	v_pk_mul_f32 v[72:73], v[76:77], v[72:73]
	v_pk_mul_f32 v[66:67], v[70:71], v[66:67]
	v_pk_mul_f32 v[64:65], v[68:69], v[64:65]
	v_pk_mul_f32 v[58:59], v[62:63], v[58:59]
	v_pk_mul_f32 v[56:57], v[60:61], v[56:57]
	v_pk_mul_f32 v[50:51], v[54:55], v[50:51]
	v_pk_mul_f32 v[48:49], v[52:53], v[48:49]
	v_pk_mul_f32 v[42:43], v[46:47], v[42:43]
	v_pk_mul_f32 v[40:41], v[44:45], v[40:41]
	v_pk_mul_f32 v[34:35], v[38:39], v[34:35]
	v_pk_mul_f32 v[32:33], v[36:37], v[32:33]
	v_pk_mul_f32 v[26:27], v[30:31], v[26:27]
	v_pk_mul_f32 v[24:25], v[28:29], v[24:25]
	v_pk_mul_f32 v[18:19], v[22:23], v[18:19]
	v_pk_mul_f32 v[16:17], v[20:21], v[16:17]
	v_pk_mul_f32 v[10:11], v[14:15], v[10:11]
	v_pk_mul_f32 v[8:9], v[12:13], v[8:9]
	v_pk_mul_f32 v[2:3], v[6:7], v[2:3]
	v_pk_mul_f32 v[0:1], v[4:5], v[0:1]
	s_waitcnt vmcnt(7)
	v_cvt_f32_u32_e32 v171, v171
	v_cvt_f32_u32_e32 v170, v170
	v_fmac_f32_e32 v170, 0x4f800000, v171
	v_fmamk_f32 v170, v170, 0x30000000, v234
	v_rsq_f32_e32 v178, v170
	s_nop 0
	v_mul_f32_e32 v174, 0xbfb8aa3b, v178
	v_pk_mul_f32 v[172:173], v[150:151], v[174:175] op_sel_hi:[1,0]
	v_pk_mul_f32 v[170:171], v[148:149], v[174:175] op_sel_hi:[1,0]
	v_pk_mul_f32 v[176:177], v[142:143], v[174:175] op_sel_hi:[1,0]
	v_pk_mul_f32 v[174:175], v[140:141], v[174:175] op_sel_hi:[1,0]
	v_mul_f32_e32 v178, v178, v178
	v_pk_mul_f32 v[180:181], v[146:147], v[178:179] op_sel_hi:[1,0]
	v_exp_f32_e32 v170, v170
	v_exp_f32_e32 v174, v174
	v_exp_f32_e32 v171, v171
	v_exp_f32_e32 v175, v175
	v_exp_f32_e32 v172, v172
	v_exp_f32_e32 v176, v176
	v_exp_f32_e32 v173, v173
	v_exp_f32_e32 v177, v177
	v_pk_mul_f32 v[182:183], v[144:145], v[178:179] op_sel_hi:[1,0]
	v_pk_add_f32 v[144:145], v[170:171], 1.0 op_sel_hi:[1,0]
	v_pk_add_f32 v[146:147], v[172:173], 1.0 op_sel_hi:[1,0]
	v_pk_add_f32 v[150:151], v[176:177], 1.0 op_sel_hi:[1,0]
	v_pk_add_f32 v[148:149], v[174:175], 1.0 op_sel_hi:[1,0]
	v_pk_mul_f32 v[138:139], v[138:139], v[178:179] op_sel_hi:[1,0]
	v_pk_mul_f32 v[136:137], v[136:137], v[178:179] op_sel_hi:[1,0]
	v_rcp_f32_e32 v144, v144
	v_rcp_f32_e32 v148, v148
	v_rcp_f32_e32 v145, v145
	v_rcp_f32_e32 v149, v149
	v_rcp_f32_e32 v146, v146
	v_rcp_f32_e32 v150, v150
	v_rcp_f32_e32 v147, v147
	v_rcp_f32_e32 v151, v151
	s_nop 0
	v_pk_mul_f32 v[140:141], v[180:181], v[146:147]
	v_pk_mul_f32 v[142:143], v[182:183], v[144:145]
	v_pk_mul_f32 v[144:145], v[138:139], v[150:151]
	v_pk_mul_f32 v[138:139], v[136:137], v[148:149]
	v_cvt_pk_bf16_f32 v136, v142, v143
	v_cvt_pk_bf16_f32 v137, v140, v141
	v_cvt_pk_bf16_f32 v138, v138, v139
	v_cvt_pk_bf16_f32 v139, v144, v145
	v_lshl_add_u64 v[140:141], s[36:37], 0, v[82:83]
	global_store_dwordx4 v[140:141], v[136:139], off
	s_waitcnt vmcnt(7)
	s_nop 0
	v_cvt_f32_u32_e32 v136, v165
	v_cvt_f32_u32_e32 v137, v164
	v_fmac_f32_e32 v137, 0x4f800000, v136
	v_fmamk_f32 v136, v137, 0x30000000, v234
	v_rsq_f32_e32 v144, v136
	s_nop 0
	v_mul_f32_e32 v140, 0xbfb8aa3b, v144
	v_pk_mul_f32 v[138:139], v[134:135], v[140:141] op_sel_hi:[1,0]
	v_pk_mul_f32 v[136:137], v[132:133], v[140:141] op_sel_hi:[1,0]
	v_pk_mul_f32 v[142:143], v[126:127], v[140:141] op_sel_hi:[1,0]
	v_pk_mul_f32 v[140:141], v[124:125], v[140:141] op_sel_hi:[1,0]
	v_mul_f32_e32 v144, v144, v144
	v_pk_mul_f32 v[146:147], v[130:131], v[144:145] op_sel_hi:[1,0]
	v_exp_f32_e32 v136, v136
	v_exp_f32_e32 v140, v140
	v_exp_f32_e32 v137, v137
	v_exp_f32_e32 v141, v141
	v_exp_f32_e32 v138, v138
	v_exp_f32_e32 v142, v142
	v_exp_f32_e32 v139, v139
	v_exp_f32_e32 v143, v143
	v_pk_mul_f32 v[148:149], v[128:129], v[144:145] op_sel_hi:[1,0]
	v_pk_add_f32 v[128:129], v[136:137], 1.0 op_sel_hi:[1,0]
	v_pk_add_f32 v[130:131], v[138:139], 1.0 op_sel_hi:[1,0]
	v_pk_add_f32 v[134:135], v[142:143], 1.0 op_sel_hi:[1,0]
	v_pk_add_f32 v[132:133], v[140:141], 1.0 op_sel_hi:[1,0]
	v_pk_mul_f32 v[122:123], v[122:123], v[144:145] op_sel_hi:[1,0]
	v_pk_mul_f32 v[120:121], v[120:121], v[144:145] op_sel_hi:[1,0]
	v_rcp_f32_e32 v128, v128
	v_rcp_f32_e32 v132, v132
	v_rcp_f32_e32 v129, v129
	v_rcp_f32_e32 v133, v133
	v_rcp_f32_e32 v130, v130
	v_rcp_f32_e32 v134, v134
	v_rcp_f32_e32 v131, v131
	v_rcp_f32_e32 v135, v135
	s_nop 0
	v_pk_mul_f32 v[124:125], v[146:147], v[130:131]
	v_pk_mul_f32 v[126:127], v[148:149], v[128:129]
	v_pk_mul_f32 v[128:129], v[122:123], v[134:135]
	v_pk_mul_f32 v[122:123], v[120:121], v[132:133]
	v_cvt_pk_bf16_f32 v120, v126, v127
	v_cvt_pk_bf16_f32 v121, v124, v125
	v_cvt_pk_bf16_f32 v122, v122, v123
	v_cvt_pk_bf16_f32 v123, v128, v129
	v_lshl_add_u64 v[124:125], s[4:5], 0, v[82:83]
	global_store_dwordx4 v[124:125], v[120:123], off
	s_or_b32 s4, s33, 0x1000
	s_add_u32 s4, s20, s4
	s_waitcnt vmcnt(7)
	v_cvt_f32_u32_e32 v120, v163
	v_cvt_f32_u32_e32 v121, v162
	s_addc_u32 s5, s68, 0
	v_fmac_f32_e32 v121, 0x4f800000, v120
	v_fmamk_f32 v120, v121, 0x30000000, v234
	v_rsq_f32_e32 v128, v120
	s_nop 0
	v_mul_f32_e32 v124, 0xbfb8aa3b, v128
	v_pk_mul_f32 v[122:123], v[118:119], v[124:125] op_sel_hi:[1,0]
	v_pk_mul_f32 v[120:121], v[116:117], v[124:125] op_sel_hi:[1,0]
	v_pk_mul_f32 v[126:127], v[110:111], v[124:125] op_sel_hi:[1,0]
	v_pk_mul_f32 v[124:125], v[108:109], v[124:125] op_sel_hi:[1,0]
	v_mul_f32_e32 v128, v128, v128
	v_pk_mul_f32 v[130:131], v[114:115], v[128:129] op_sel_hi:[1,0]
	v_exp_f32_e32 v120, v120
	v_exp_f32_e32 v124, v124
	v_exp_f32_e32 v121, v121
	v_exp_f32_e32 v125, v125
	v_exp_f32_e32 v122, v122
	v_exp_f32_e32 v126, v126
	v_exp_f32_e32 v123, v123
	v_exp_f32_e32 v127, v127
	v_pk_mul_f32 v[132:133], v[112:113], v[128:129] op_sel_hi:[1,0]
	v_pk_add_f32 v[112:113], v[120:121], 1.0 op_sel_hi:[1,0]
	v_pk_add_f32 v[114:115], v[122:123], 1.0 op_sel_hi:[1,0]
	v_pk_add_f32 v[118:119], v[126:127], 1.0 op_sel_hi:[1,0]
	v_pk_add_f32 v[116:117], v[124:125], 1.0 op_sel_hi:[1,0]
	v_pk_mul_f32 v[106:107], v[106:107], v[128:129] op_sel_hi:[1,0]
	v_pk_mul_f32 v[104:105], v[104:105], v[128:129] op_sel_hi:[1,0]
	v_rcp_f32_e32 v112, v112
	v_rcp_f32_e32 v116, v116
	v_rcp_f32_e32 v113, v113
	v_rcp_f32_e32 v117, v117
	v_rcp_f32_e32 v114, v114
	v_rcp_f32_e32 v118, v118
	v_rcp_f32_e32 v115, v115
	v_rcp_f32_e32 v119, v119
	s_nop 0
	v_pk_mul_f32 v[108:109], v[130:131], v[114:115]
	v_pk_mul_f32 v[110:111], v[132:133], v[112:113]
	v_pk_mul_f32 v[112:113], v[106:107], v[118:119]
	v_pk_mul_f32 v[106:107], v[104:105], v[116:117]
	v_cvt_pk_bf16_f32 v104, v110, v111
	v_cvt_pk_bf16_f32 v105, v108, v109
	v_cvt_pk_bf16_f32 v106, v106, v107
	v_cvt_pk_bf16_f32 v107, v112, v113
	v_lshl_add_u64 v[108:109], s[4:5], 0, v[82:83]
	global_store_dwordx4 v[108:109], v[104:107], off
	s_or_b32 s4, s33, 0x1800
	s_add_u32 s4, s20, s4
	s_waitcnt vmcnt(7)
	v_cvt_f32_u32_e32 v104, v161
	v_cvt_f32_u32_e32 v105, v160
	s_addc_u32 s5, s68, 0
	v_fmac_f32_e32 v105, 0x4f800000, v104
	v_fmamk_f32 v104, v105, 0x30000000, v234
	v_rsq_f32_e32 v112, v104
	s_nop 0
	v_mul_f32_e32 v108, 0xbfb8aa3b, v112
	v_pk_mul_f32 v[106:107], v[78:79], v[108:109] op_sel_hi:[1,0]
	v_pk_mul_f32 v[104:105], v[76:77], v[108:109] op_sel_hi:[1,0]
	v_pk_mul_f32 v[110:111], v[70:71], v[108:109] op_sel_hi:[1,0]
	v_pk_mul_f32 v[108:109], v[68:69], v[108:109] op_sel_hi:[1,0]
	v_mul_f32_e32 v112, v112, v112
	v_pk_mul_f32 v[114:115], v[74:75], v[112:113] op_sel_hi:[1,0]
	v_exp_f32_e32 v104, v104
	v_exp_f32_e32 v108, v108
	v_exp_f32_e32 v105, v105
	v_exp_f32_e32 v109, v109
	v_exp_f32_e32 v106, v106
	v_exp_f32_e32 v110, v110
	v_exp_f32_e32 v107, v107
	v_exp_f32_e32 v111, v111
	v_pk_mul_f32 v[116:117], v[72:73], v[112:113] op_sel_hi:[1,0]
	v_pk_add_f32 v[72:73], v[104:105], 1.0 op_sel_hi:[1,0]
	v_pk_add_f32 v[74:75], v[106:107], 1.0 op_sel_hi:[1,0]
	v_pk_add_f32 v[78:79], v[110:111], 1.0 op_sel_hi:[1,0]
	v_pk_add_f32 v[76:77], v[108:109], 1.0 op_sel_hi:[1,0]
	v_pk_mul_f32 v[66:67], v[66:67], v[112:113] op_sel_hi:[1,0]
	v_pk_mul_f32 v[64:65], v[64:65], v[112:113] op_sel_hi:[1,0]
	v_rcp_f32_e32 v72, v72
	v_rcp_f32_e32 v76, v76
	v_rcp_f32_e32 v73, v73
	v_rcp_f32_e32 v77, v77
	v_rcp_f32_e32 v74, v74
	v_rcp_f32_e32 v78, v78
	v_rcp_f32_e32 v75, v75
	v_rcp_f32_e32 v79, v79
	s_nop 0
	v_pk_mul_f32 v[68:69], v[114:115], v[74:75]
	v_pk_mul_f32 v[70:71], v[116:117], v[72:73]
	v_pk_mul_f32 v[72:73], v[66:67], v[78:79]
	v_pk_mul_f32 v[66:67], v[64:65], v[76:77]
	v_cvt_pk_bf16_f32 v64, v70, v71
	v_cvt_pk_bf16_f32 v65, v68, v69
	v_cvt_pk_bf16_f32 v66, v66, v67
	v_cvt_pk_bf16_f32 v67, v72, v73
	v_lshl_add_u64 v[68:69], s[4:5], 0, v[82:83]
	global_store_dwordx4 v[68:69], v[64:67], off
	s_add_i32 s4, s33, 0x160000
	s_add_u32 s4, s20, s4
	s_waitcnt vmcnt(7)
	v_cvt_f32_u32_e32 v64, v159
	v_cvt_f32_u32_e32 v65, v158
	s_addc_u32 s5, s68, 0
	v_fmac_f32_e32 v65, 0x4f800000, v64
	v_fmamk_f32 v64, v65, 0x30000000, v234
	v_rsq_f32_e32 v72, v64
	s_nop 0
	v_mul_f32_e32 v68, 0xbfb8aa3b, v72
	v_pk_mul_f32 v[66:67], v[62:63], v[68:69] op_sel_hi:[1,0]
	v_pk_mul_f32 v[64:65], v[60:61], v[68:69] op_sel_hi:[1,0]
	v_pk_mul_f32 v[70:71], v[54:55], v[68:69] op_sel_hi:[1,0]
	v_pk_mul_f32 v[68:69], v[52:53], v[68:69] op_sel_hi:[1,0]
	v_mul_f32_e32 v72, v72, v72
	v_pk_mul_f32 v[74:75], v[58:59], v[72:73] op_sel_hi:[1,0]
	v_exp_f32_e32 v64, v64
	v_exp_f32_e32 v68, v68
	v_exp_f32_e32 v65, v65
	v_exp_f32_e32 v69, v69
	v_exp_f32_e32 v66, v66
	v_exp_f32_e32 v70, v70
	v_exp_f32_e32 v67, v67
	v_exp_f32_e32 v71, v71
	v_pk_mul_f32 v[76:77], v[56:57], v[72:73] op_sel_hi:[1,0]
	v_pk_add_f32 v[56:57], v[64:65], 1.0 op_sel_hi:[1,0]
	v_pk_add_f32 v[58:59], v[66:67], 1.0 op_sel_hi:[1,0]
	v_pk_add_f32 v[62:63], v[70:71], 1.0 op_sel_hi:[1,0]
	v_pk_add_f32 v[60:61], v[68:69], 1.0 op_sel_hi:[1,0]
	v_pk_mul_f32 v[50:51], v[50:51], v[72:73] op_sel_hi:[1,0]
	v_pk_mul_f32 v[48:49], v[48:49], v[72:73] op_sel_hi:[1,0]
	v_rcp_f32_e32 v56, v56
	v_rcp_f32_e32 v60, v60
	v_rcp_f32_e32 v57, v57
	v_rcp_f32_e32 v61, v61
	v_rcp_f32_e32 v58, v58
	v_rcp_f32_e32 v62, v62
	v_rcp_f32_e32 v59, v59
	v_rcp_f32_e32 v63, v63
	s_nop 0
	v_pk_mul_f32 v[52:53], v[74:75], v[58:59]
	v_pk_mul_f32 v[54:55], v[76:77], v[56:57]
	v_pk_mul_f32 v[56:57], v[50:51], v[62:63]
	v_pk_mul_f32 v[50:51], v[48:49], v[60:61]
	v_cvt_pk_bf16_f32 v48, v54, v55
	v_cvt_pk_bf16_f32 v49, v52, v53
	v_cvt_pk_bf16_f32 v50, v50, v51
	v_cvt_pk_bf16_f32 v51, v56, v57
	v_lshl_add_u64 v[52:53], s[4:5], 0, v[82:83]
	global_store_dwordx4 v[52:53], v[48:51], off
	s_add_i32 s4, s33, 0x160800
	s_add_u32 s4, s20, s4
	s_waitcnt vmcnt(7)
	v_cvt_f32_u32_e32 v48, v157
	v_cvt_f32_u32_e32 v49, v156
	s_addc_u32 s5, s68, 0
	v_fmac_f32_e32 v49, 0x4f800000, v48
	v_fmamk_f32 v48, v49, 0x30000000, v234
	v_rsq_f32_e32 v56, v48
	s_nop 0
	v_mul_f32_e32 v52, 0xbfb8aa3b, v56
	v_pk_mul_f32 v[50:51], v[46:47], v[52:53] op_sel_hi:[1,0]
	v_pk_mul_f32 v[48:49], v[44:45], v[52:53] op_sel_hi:[1,0]
	v_pk_mul_f32 v[54:55], v[38:39], v[52:53] op_sel_hi:[1,0]
	v_pk_mul_f32 v[52:53], v[36:37], v[52:53] op_sel_hi:[1,0]
	v_mul_f32_e32 v56, v56, v56
	v_pk_mul_f32 v[58:59], v[42:43], v[56:57] op_sel_hi:[1,0]
	v_exp_f32_e32 v48, v48
	v_exp_f32_e32 v52, v52
	v_exp_f32_e32 v49, v49
	v_exp_f32_e32 v53, v53
	v_exp_f32_e32 v50, v50
	v_exp_f32_e32 v54, v54
	v_exp_f32_e32 v51, v51
	v_exp_f32_e32 v55, v55
	v_pk_mul_f32 v[60:61], v[40:41], v[56:57] op_sel_hi:[1,0]
	v_pk_add_f32 v[40:41], v[48:49], 1.0 op_sel_hi:[1,0]
	v_pk_add_f32 v[42:43], v[50:51], 1.0 op_sel_hi:[1,0]
	v_pk_add_f32 v[46:47], v[54:55], 1.0 op_sel_hi:[1,0]
	v_pk_add_f32 v[44:45], v[52:53], 1.0 op_sel_hi:[1,0]
	v_pk_mul_f32 v[34:35], v[34:35], v[56:57] op_sel_hi:[1,0]
	v_pk_mul_f32 v[32:33], v[32:33], v[56:57] op_sel_hi:[1,0]
	v_rcp_f32_e32 v40, v40
	v_rcp_f32_e32 v44, v44
	v_rcp_f32_e32 v41, v41
	v_rcp_f32_e32 v45, v45
	v_rcp_f32_e32 v42, v42
	v_rcp_f32_e32 v46, v46
	v_rcp_f32_e32 v43, v43
	v_rcp_f32_e32 v47, v47
	s_nop 0
	v_pk_mul_f32 v[36:37], v[58:59], v[42:43]
	v_pk_mul_f32 v[38:39], v[60:61], v[40:41]
	v_pk_mul_f32 v[40:41], v[34:35], v[46:47]
	v_pk_mul_f32 v[34:35], v[32:33], v[44:45]
	v_cvt_pk_bf16_f32 v32, v38, v39
	v_cvt_pk_bf16_f32 v33, v36, v37
	v_cvt_pk_bf16_f32 v34, v34, v35
	v_cvt_pk_bf16_f32 v35, v40, v41
	v_lshl_add_u64 v[36:37], s[4:5], 0, v[82:83]
	global_store_dwordx4 v[36:37], v[32:35], off
	s_add_i32 s4, s33, 0x161000
	s_add_u32 s4, s20, s4
	s_waitcnt vmcnt(7)
	v_cvt_f32_u32_e32 v32, v155
	v_cvt_f32_u32_e32 v33, v154
	s_addc_u32 s5, s68, 0
	s_add_i32 s33, s33, 0x161800
	v_fmac_f32_e32 v33, 0x4f800000, v32
	v_fmamk_f32 v32, v33, 0x30000000, v234
	v_rsq_f32_e32 v40, v32
	s_nop 0
	v_mul_f32_e32 v36, 0xbfb8aa3b, v40
	v_pk_mul_f32 v[34:35], v[30:31], v[36:37] op_sel_hi:[1,0]
	v_pk_mul_f32 v[32:33], v[28:29], v[36:37] op_sel_hi:[1,0]
	v_pk_mul_f32 v[38:39], v[22:23], v[36:37] op_sel_hi:[1,0]
	v_pk_mul_f32 v[36:37], v[20:21], v[36:37] op_sel_hi:[1,0]
	v_mul_f32_e32 v40, v40, v40
	v_pk_mul_f32 v[42:43], v[26:27], v[40:41] op_sel_hi:[1,0]
	v_exp_f32_e32 v32, v32
	v_exp_f32_e32 v36, v36
	v_exp_f32_e32 v33, v33
	v_exp_f32_e32 v37, v37
	v_exp_f32_e32 v34, v34
	v_exp_f32_e32 v38, v38
	v_exp_f32_e32 v35, v35
	v_exp_f32_e32 v39, v39
	v_pk_mul_f32 v[44:45], v[24:25], v[40:41] op_sel_hi:[1,0]
	v_pk_add_f32 v[24:25], v[32:33], 1.0 op_sel_hi:[1,0]
	v_pk_add_f32 v[26:27], v[34:35], 1.0 op_sel_hi:[1,0]
	v_pk_add_f32 v[30:31], v[38:39], 1.0 op_sel_hi:[1,0]
	v_pk_add_f32 v[28:29], v[36:37], 1.0 op_sel_hi:[1,0]
	v_pk_mul_f32 v[18:19], v[18:19], v[40:41] op_sel_hi:[1,0]
	v_pk_mul_f32 v[16:17], v[16:17], v[40:41] op_sel_hi:[1,0]
	v_rcp_f32_e32 v24, v24
	v_rcp_f32_e32 v28, v28
	v_rcp_f32_e32 v25, v25
	v_rcp_f32_e32 v29, v29
	v_rcp_f32_e32 v26, v26
	v_rcp_f32_e32 v30, v30
	v_rcp_f32_e32 v27, v27
	v_rcp_f32_e32 v31, v31
	s_nop 0
	v_pk_mul_f32 v[20:21], v[42:43], v[26:27]
	v_pk_mul_f32 v[22:23], v[44:45], v[24:25]
	v_pk_mul_f32 v[24:25], v[18:19], v[30:31]
	v_pk_mul_f32 v[18:19], v[16:17], v[28:29]
	v_cvt_pk_bf16_f32 v16, v22, v23
	v_cvt_pk_bf16_f32 v17, v20, v21
	v_cvt_pk_bf16_f32 v18, v18, v19
	v_cvt_pk_bf16_f32 v19, v24, v25
	v_lshl_add_u64 v[20:21], s[4:5], 0, v[82:83]
	global_store_dwordx4 v[20:21], v[16:19], off
	s_add_u32 s4, s20, s33
	s_addc_u32 s5, s68, 0
	s_waitcnt vmcnt(7)
	v_cvt_f32_u32_e32 v16, v153
	v_cvt_f32_u32_e32 v17, v152
	s_andn2_b64 vcc, exec, s[38:39]
	v_fmac_f32_e32 v17, 0x4f800000, v16
	v_fmamk_f32 v16, v17, 0x30000000, v234
	v_rsq_f32_e32 v24, v16
	s_nop 0
	v_mul_f32_e32 v20, 0xbfb8aa3b, v24
	v_pk_mul_f32 v[18:19], v[14:15], v[20:21] op_sel_hi:[1,0]
	v_pk_mul_f32 v[16:17], v[12:13], v[20:21] op_sel_hi:[1,0]
	v_pk_mul_f32 v[22:23], v[6:7], v[20:21] op_sel_hi:[1,0]
	v_pk_mul_f32 v[20:21], v[4:5], v[20:21] op_sel_hi:[1,0]
	v_mul_f32_e32 v24, v24, v24
	v_pk_mul_f32 v[26:27], v[10:11], v[24:25] op_sel_hi:[1,0]
	v_exp_f32_e32 v16, v16
	v_exp_f32_e32 v20, v20
	v_exp_f32_e32 v17, v17
	v_exp_f32_e32 v21, v21
	v_exp_f32_e32 v18, v18
	v_exp_f32_e32 v22, v22
	v_exp_f32_e32 v19, v19
	v_exp_f32_e32 v23, v23
	v_pk_mul_f32 v[28:29], v[8:9], v[24:25] op_sel_hi:[1,0]
	v_pk_add_f32 v[8:9], v[16:17], 1.0 op_sel_hi:[1,0]
	v_pk_add_f32 v[10:11], v[18:19], 1.0 op_sel_hi:[1,0]
	v_pk_add_f32 v[14:15], v[22:23], 1.0 op_sel_hi:[1,0]
	v_pk_add_f32 v[12:13], v[20:21], 1.0 op_sel_hi:[1,0]
	v_pk_mul_f32 v[2:3], v[2:3], v[24:25] op_sel_hi:[1,0]
	v_pk_mul_f32 v[0:1], v[0:1], v[24:25] op_sel_hi:[1,0]
	v_rcp_f32_e32 v8, v8
	v_rcp_f32_e32 v12, v12
	v_rcp_f32_e32 v9, v9
	v_rcp_f32_e32 v13, v13
	v_rcp_f32_e32 v10, v10
	v_rcp_f32_e32 v14, v14
	v_rcp_f32_e32 v11, v11
	v_rcp_f32_e32 v15, v15
	s_nop 0
	v_pk_mul_f32 v[4:5], v[26:27], v[10:11]
	v_pk_mul_f32 v[6:7], v[28:29], v[8:9]
	v_pk_mul_f32 v[8:9], v[2:3], v[14:15]
	v_pk_mul_f32 v[2:3], v[0:1], v[12:13]
	v_cvt_pk_bf16_f32 v0, v6, v7
	v_cvt_pk_bf16_f32 v1, v4, v5
	v_cvt_pk_bf16_f32 v2, v2, v3
	v_cvt_pk_bf16_f32 v3, v8, v9
	v_lshl_add_u64 v[4:5], s[4:5], 0, v[82:83]
	s_mov_b64 s[4:5], -1
	global_store_dwordx4 v[4:5], v[0:3], off
	s_cbranch_vccnz .LBB0_791
	s_mov_b32 s101, 0
	s_andn2_b64 vcc, exec, s[0:1]
	s_cbranch_vccnz .LBB0_790
	s_mov_b32 s101, 1
	s_branch .LBB0_790
